# P0 grid barrier: two-level arrival (32-block group counter, last of a group adds 32 to the chip-wide counter)
# speedup vs baseline: 1.0351x; 1.0091x over previous
; __device__ __forceinline__ void grid_bar(unsigned* ctr, unsigned target, bool leader) {
;     asm volatile("s_waitcnt vmcnt(0) lgkmcnt(0)" ::: "memory");
;     __syncthreads();
;     if (leader) {
;         __builtin_amdgcn_fence(__ATOMIC_RELEASE, "agent");
;         asm volatile("s_waitcnt vmcnt(0)" ::: "memory");
;         __hip_atomic_fetch_add(ctr, 1u, __ATOMIC_RELAXED, __HIP_MEMORY_SCOPE_AGENT);
;         while (__hip_atomic_load(ctr, __ATOMIC_RELAXED, __HIP_MEMORY_SCOPE_AGENT) < target) __builtin_amdgcn_s_sleep(2);
.LBB0_207:
	s_waitcnt vmcnt(0) lgkmcnt(0)
	s_waitcnt lgkmcnt(0)
	s_barrier
	s_and_saveexec_b64 s[6:7], s[8:9]
	s_cbranch_execz .LBB0_213
	s_mov_b64 s[8:9], exec
	buffer_wbl2 sc1
	s_waitcnt vmcnt(0)
	s_waitcnt vmcnt(0)
	v_mbcnt_lo_u32_b32 v0, s8, 0
	v_mbcnt_hi_u32_b32 v0, s9, v0
	v_cmp_eq_u32_e32 vcc, 0, v0
	s_and_saveexec_b64 s[10:11], vcc
	s_cbranch_execz .LBB0_210
	s_cmp_eq_u32 s20, 0x100
	s_cbranch_scc0 .Lhb_flat
	s_and_b32 s3, s2, 7
	s_lshl_b32 s3, s3, 8
	s_addk_i32 s3, 0x140
	v_mov_b32_e32 v0, s3
	v_mov_b32_e32 v1, 1
	global_atomic_add v2, v0, v1, s[4:5] sc0
	s_waitcnt vmcnt(0)
	v_cmp_eq_u32_e32 vcc, 31, v2
	s_cbranch_vccz .LBB0_210
	v_mov_b32_e32 v0, 0
	v_mov_b32_e32 v1, 32
	global_atomic_add v0, v1, s[4:5]
	s_branch .LBB0_210
.Lhb_flat:
	s_bcnt1_i32_b64 s3, s[8:9]
	v_mov_b32_e32 v0, 0
	v_mov_b32_e32 v1, s3
	global_atomic_add v0, v1, s[4:5]
